# combo6 plus batched decay/max pair loads in the mLSTM state-scan phase
# speedup vs baseline: 1.0091x; 1.0091x over previous
.LBB0_535:
	v_add_u32_e32 v2, 0xfffe0000, v53
	s_mov_b32 s4, 0x20000
	v_lshrrev_b32_e32 v2, 7, v2
	v_ashrrev_i32_e32 v3, 11, v53
	v_cmp_gt_i32_e64 s[4:5], s4, v53
	s_mov_b32 s8, 0x1ffff
	v_cmp_lt_i32_e32 vcc, s8, v53
	v_cndmask_b32_e64 v6, v2, v3, s[4:5]
	v_lshlrev_b32_e32 v2, 5, v6
	v_ashrrev_i32_e32 v3, 31, v2
	v_lshl_add_u64 v[2:3], v[2:3], 2, s[12:13]
	global_load_dwordx2 v[212:213], v[2:3], off
	global_load_dwordx2 v[214:215], v[2:3], off offset:8
	global_load_dwordx2 v[216:217], v[2:3], off offset:16
	global_load_dwordx2 v[218:219], v[2:3], off offset:24
	global_load_dwordx2 v[220:221], v[2:3], off offset:32
	global_load_dwordx2 v[222:223], v[2:3], off offset:40
	global_load_dwordx2 v[224:225], v[2:3], off offset:48
	global_load_dwordx2 v[226:227], v[2:3], off offset:56
	global_load_dwordx2 v[228:229], v[2:3], off offset:64
	global_load_dwordx2 v[230:231], v[2:3], off offset:72
	global_load_dwordx2 v[232:233], v[2:3], off offset:80
	global_load_dwordx2 v[234:235], v[2:3], off offset:88
	global_load_dwordx2 v[236:237], v[2:3], off offset:96
	global_load_dwordx2 v[238:239], v[2:3], off offset:104
	global_load_dwordx2 v[240:241], v[2:3], off offset:112
	s_waitcnt vmcnt(0)
	v_mov_b64_e32 v[4:5], v[212:213]
	v_and_b32_e32 v3, 0x7ff, v53
	v_lshlrev_b32_e32 v2, 4, v6
	v_cmp_eq_u32_e64 s[8:9], 0, v3
	s_and_b64 s[4:5], s[4:5], s[8:9]
	v_ashrrev_i32_e32 v3, 31, v2
	s_and_saveexec_b64 s[8:9], s[4:5]
	s_cbranch_execz .LBB0_537
	v_lshl_add_u64 v[6:7], v[2:3], 2, s[14:15]
	v_mov_b32_e32 v8, 0xf149f2ca
	global_store_dword v[6:7], v8, off sc1
.LBB0_537:
	s_or_b64 exec, exec, s[8:9]
	v_or_b32_e32 v8, 1, v2
	v_lshlrev_b32_e32 v6, 1, v8
	v_ashrrev_i32_e32 v7, 31, v6
	v_lshl_add_u64 v[6:7], v[6:7], 2, s[12:13]
	v_mov_b64_e32 v[6:7], v[214:215]
	v_add_f32_e32 v38, 0xf149f2ca, v4
	v_max_f32_e32 v4, v5, v5
	v_max_f32_e32 v4, v38, v4
	s_and_saveexec_b64 s[8:9], s[4:5]
	s_cbranch_execz .LBB0_539
	v_ashrrev_i32_e32 v9, 31, v8
	v_lshl_add_u64 v[8:9], v[8:9], 2, s[14:15]
	global_store_dword v[8:9], v4, off sc1
.LBB0_539:
	s_or_b64 exec, exec, s[8:9]
	v_or_b32_e32 v10, 2, v2
	v_lshlrev_b32_e32 v8, 1, v10
	v_ashrrev_i32_e32 v9, 31, v8
	v_lshl_add_u64 v[8:9], v[8:9], 2, s[12:13]
	v_mov_b64_e32 v[8:9], v[216:217]
	v_add_f32_e32 v39, v4, v6
	v_max_f32_e32 v6, v7, v7
	v_max_f32_e32 v6, v39, v6
	s_and_saveexec_b64 s[8:9], s[4:5]
	s_cbranch_execz .LBB0_541
	v_ashrrev_i32_e32 v11, 31, v10
	v_lshl_add_u64 v[10:11], v[10:11], 2, s[14:15]
	global_store_dword v[10:11], v6, off sc1
.LBB0_541:
	s_or_b64 exec, exec, s[8:9]
	v_or_b32_e32 v12, 3, v2
	v_lshlrev_b32_e32 v10, 1, v12
	v_ashrrev_i32_e32 v11, 31, v10
	v_lshl_add_u64 v[10:11], v[10:11], 2, s[12:13]
	v_mov_b64_e32 v[10:11], v[218:219]
	v_add_f32_e32 v40, v6, v8
	v_max_f32_e32 v8, v9, v9
	v_max_f32_e32 v8, v40, v8
	s_and_saveexec_b64 s[8:9], s[4:5]
	s_cbranch_execz .LBB0_543
	v_ashrrev_i32_e32 v13, 31, v12
	v_lshl_add_u64 v[12:13], v[12:13], 2, s[14:15]
	global_store_dword v[12:13], v8, off sc1
.LBB0_543:
	s_or_b64 exec, exec, s[8:9]
	v_or_b32_e32 v14, 4, v2
	v_lshlrev_b32_e32 v12, 1, v14
	v_ashrrev_i32_e32 v13, 31, v12
	v_lshl_add_u64 v[12:13], v[12:13], 2, s[12:13]
	v_mov_b64_e32 v[12:13], v[220:221]
	v_add_f32_e32 v41, v8, v10
	v_max_f32_e32 v10, v11, v11
	v_max_f32_e32 v10, v41, v10
	s_and_saveexec_b64 s[8:9], s[4:5]
	s_cbranch_execz .LBB0_545
	v_ashrrev_i32_e32 v15, 31, v14
	v_lshl_add_u64 v[14:15], v[14:15], 2, s[14:15]
	global_store_dword v[14:15], v10, off sc1
.LBB0_545:
	s_or_b64 exec, exec, s[8:9]
	v_or_b32_e32 v16, 5, v2
	v_lshlrev_b32_e32 v14, 1, v16
	v_ashrrev_i32_e32 v15, 31, v14
	v_lshl_add_u64 v[14:15], v[14:15], 2, s[12:13]
	v_mov_b64_e32 v[14:15], v[222:223]
	v_add_f32_e32 v42, v10, v12
	v_max_f32_e32 v12, v13, v13
	v_max_f32_e32 v12, v42, v12
	s_and_saveexec_b64 s[8:9], s[4:5]
	s_cbranch_execz .LBB0_547
	v_ashrrev_i32_e32 v17, 31, v16
	v_lshl_add_u64 v[16:17], v[16:17], 2, s[14:15]
	global_store_dword v[16:17], v12, off sc1
.LBB0_547:
	s_or_b64 exec, exec, s[8:9]
	v_or_b32_e32 v18, 6, v2
	v_lshlrev_b32_e32 v16, 1, v18
	v_ashrrev_i32_e32 v17, 31, v16
	v_lshl_add_u64 v[16:17], v[16:17], 2, s[12:13]
	v_mov_b64_e32 v[16:17], v[224:225]
	v_add_f32_e32 v43, v12, v14
	v_max_f32_e32 v14, v15, v15
	v_max_f32_e32 v14, v43, v14
	s_and_saveexec_b64 s[8:9], s[4:5]
	s_cbranch_execz .LBB0_549
	v_ashrrev_i32_e32 v19, 31, v18
	v_lshl_add_u64 v[18:19], v[18:19], 2, s[14:15]
	global_store_dword v[18:19], v14, off sc1
.LBB0_549:
	s_or_b64 exec, exec, s[8:9]
	v_or_b32_e32 v20, 7, v2
	v_lshlrev_b32_e32 v18, 1, v20
	v_ashrrev_i32_e32 v19, 31, v18
	v_lshl_add_u64 v[18:19], v[18:19], 2, s[12:13]
	v_mov_b64_e32 v[18:19], v[226:227]
	v_add_f32_e32 v44, v14, v16
	v_max_f32_e32 v16, v17, v17
	v_max_f32_e32 v16, v44, v16
	s_and_saveexec_b64 s[8:9], s[4:5]
	s_cbranch_execz .LBB0_551
	v_ashrrev_i32_e32 v21, 31, v20
	v_lshl_add_u64 v[20:21], v[20:21], 2, s[14:15]
	global_store_dword v[20:21], v16, off sc1
.LBB0_551:
	s_or_b64 exec, exec, s[8:9]
	v_or_b32_e32 v22, 8, v2
	v_lshlrev_b32_e32 v20, 1, v22
	v_ashrrev_i32_e32 v21, 31, v20
	v_lshl_add_u64 v[20:21], v[20:21], 2, s[12:13]
	v_mov_b64_e32 v[20:21], v[228:229]
	v_add_f32_e32 v45, v16, v18
	v_max_f32_e32 v18, v19, v19
	v_max_f32_e32 v18, v45, v18
	s_and_saveexec_b64 s[8:9], s[4:5]
	s_cbranch_execz .LBB0_553
	v_ashrrev_i32_e32 v23, 31, v22
	v_lshl_add_u64 v[22:23], v[22:23], 2, s[14:15]
	global_store_dword v[22:23], v18, off sc1
.LBB0_553:
	s_or_b64 exec, exec, s[8:9]
	v_or_b32_e32 v24, 9, v2
	v_lshlrev_b32_e32 v22, 1, v24
	v_ashrrev_i32_e32 v23, 31, v22
	v_lshl_add_u64 v[22:23], v[22:23], 2, s[12:13]
	v_mov_b64_e32 v[22:23], v[230:231]
	v_add_f32_e32 v46, v18, v20
	v_max_f32_e32 v20, v21, v21
	v_max_f32_e32 v20, v46, v20
	s_and_saveexec_b64 s[8:9], s[4:5]
	s_cbranch_execz .LBB0_555
	v_ashrrev_i32_e32 v25, 31, v24
	v_lshl_add_u64 v[24:25], v[24:25], 2, s[14:15]
	global_store_dword v[24:25], v20, off sc1
.LBB0_555:
	s_or_b64 exec, exec, s[8:9]
	v_or_b32_e32 v26, 10, v2
	v_lshlrev_b32_e32 v24, 1, v26
	v_ashrrev_i32_e32 v25, 31, v24
	v_lshl_add_u64 v[24:25], v[24:25], 2, s[12:13]
	v_mov_b64_e32 v[24:25], v[232:233]
	v_add_f32_e32 v47, v20, v22
	v_max_f32_e32 v22, v23, v23
	v_max_f32_e32 v22, v47, v22
	s_and_saveexec_b64 s[8:9], s[4:5]
	s_cbranch_execz .LBB0_557
	v_ashrrev_i32_e32 v27, 31, v26
	v_lshl_add_u64 v[26:27], v[26:27], 2, s[14:15]
	global_store_dword v[26:27], v22, off sc1
.LBB0_557:
	s_or_b64 exec, exec, s[8:9]
	v_or_b32_e32 v28, 11, v2
	v_lshlrev_b32_e32 v26, 1, v28
	v_ashrrev_i32_e32 v27, 31, v26
	v_lshl_add_u64 v[26:27], v[26:27], 2, s[12:13]
	v_mov_b64_e32 v[26:27], v[234:235]
	v_add_f32_e32 v48, v22, v24
	v_max_f32_e32 v24, v25, v25
	v_max_f32_e32 v24, v48, v24
	s_and_saveexec_b64 s[8:9], s[4:5]
	s_cbranch_execz .LBB0_559
	v_ashrrev_i32_e32 v29, 31, v28
	v_lshl_add_u64 v[28:29], v[28:29], 2, s[14:15]
	global_store_dword v[28:29], v24, off sc1
.LBB0_559:
	s_or_b64 exec, exec, s[8:9]
	v_or_b32_e32 v30, 12, v2
	v_lshlrev_b32_e32 v28, 1, v30
	v_ashrrev_i32_e32 v29, 31, v28
	v_lshl_add_u64 v[28:29], v[28:29], 2, s[12:13]
	v_mov_b64_e32 v[28:29], v[236:237]
	v_add_f32_e32 v49, v24, v26
	v_max_f32_e32 v26, v27, v27
	v_max_f32_e32 v26, v49, v26
	s_and_saveexec_b64 s[8:9], s[4:5]
	s_cbranch_execz .LBB0_561
	v_ashrrev_i32_e32 v31, 31, v30
	v_lshl_add_u64 v[30:31], v[30:31], 2, s[14:15]
	global_store_dword v[30:31], v26, off sc1
.LBB0_561:
	s_or_b64 exec, exec, s[8:9]
	v_or_b32_e32 v32, 13, v2
	v_lshlrev_b32_e32 v30, 1, v32
	v_ashrrev_i32_e32 v31, 31, v30
	v_lshl_add_u64 v[30:31], v[30:31], 2, s[12:13]
	v_mov_b64_e32 v[30:31], v[238:239]
	v_add_f32_e32 v57, v26, v28
	v_max_f32_e32 v28, v29, v29
	v_max_f32_e32 v28, v57, v28
	s_and_saveexec_b64 s[8:9], s[4:5]
	s_cbranch_execz .LBB0_563
	v_ashrrev_i32_e32 v33, 31, v32
	v_lshl_add_u64 v[32:33], v[32:33], 2, s[14:15]
	global_store_dword v[32:33], v28, off sc1
.LBB0_563:
	s_or_b64 exec, exec, s[8:9]
	v_or_b32_e32 v36, 14, v2
	v_lshlrev_b32_e32 v32, 1, v36
	v_ashrrev_i32_e32 v33, 31, v32
	v_lshl_add_u64 v[32:33], v[32:33], 2, s[12:13]
	v_mov_b64_e32 v[34:35], v[240:241]
	v_add_f32_e32 v30, v28, v30
	v_max_f32_e32 v32, v31, v31
	v_max_f32_e32 v32, v30, v32
	v_add_f32_e32 v34, v32, v34
	v_max_f32_e32 v33, v35, v35
	v_max_f32_e32 v33, v34, v33
	s_and_saveexec_b64 s[8:9], s[4:5]
	s_cbranch_execz .LBB0_565
	v_ashrrev_i32_e32 v37, 31, v36
	v_lshl_add_u64 v[36:37], v[36:37], 2, s[14:15]
	global_store_dwordx2 v[36:37], v[32:33], off sc1
